# prologue: GEMV loop 16 loads in flight; weight transposition 32 loads in flight per item
# speedup vs baseline: 1.0096x; 1.0010x over previous
; #define LDS_WAIT() asm volatile("s_waitcnt lgkmcnt(0)" ::: "memory")
; #pragma unroll 8
;     for (int i = 0; i < 32; ++i) { const int kk = 2 * i + (lane >> 5); scr[kk * 33 + (lane & 31)] = __builtin_nontemporal_load(W + (size_t)(k0 + kk) * N + n0 + (lane & 31)); }
;     LDS_WAIT(); asm volatile("" ::: "memory");
; __device__ __forceinline__ void prologue_a(const Args& a, LAS unsigned char* lds, int tid, int G) {
;     ...
;                 r -= 9728; const int kb = r / 32, nb = r % 32;
;                 transpose_item(a.in[I_WOUT] + (size_t)l * DM * DM, DM, kb * 64, nb * 32, (bf16_t*)(ws + WS_WOUT) + (size_t)l * DM * DM, DM, 0, scr, lane);
.LBB0_34:
	v_lshl_add_u64 v[110:111], v[32:33], 0, s[20:21]
	global_load_dword v78, v[110:111], off nt
	v_lshl_add_u64 v[112:113], v[30:31], 0, s[20:21]
	global_load_dword v79, v[112:113], off nt
	v_lshl_add_u64 v[114:115], v[28:29], 0, s[20:21]
	global_load_dword v80, v[114:115], off nt
	v_lshl_add_u64 v[116:117], v[26:27], 0, s[20:21]
	global_load_dword v81, v[116:117], off nt
	v_lshl_add_u64 v[110:111], v[24:25], 0, s[20:21]
	global_load_dword v82, v[110:111], off nt
	v_lshl_add_u64 v[112:113], v[22:23], 0, s[20:21]
	global_load_dword v83, v[112:113], off nt
	v_lshl_add_u64 v[114:115], v[20:21], 0, s[20:21]
	global_load_dword v84, v[114:115], off nt
	v_lshl_add_u64 v[116:117], v[18:19], 0, s[20:21]
	global_load_dword v85, v[116:117], off nt
	s_add_u32 s20, s20, 0x10000
	s_addc_u32 s21, s21, 0
	v_lshl_add_u64 v[110:111], v[32:33], 0, s[20:21]
	global_load_dword v86, v[110:111], off nt
	v_lshl_add_u64 v[112:113], v[30:31], 0, s[20:21]
	global_load_dword v87, v[112:113], off nt
	v_lshl_add_u64 v[114:115], v[28:29], 0, s[20:21]
	global_load_dword v88, v[114:115], off nt
	v_lshl_add_u64 v[116:117], v[26:27], 0, s[20:21]
	global_load_dword v89, v[116:117], off nt
	v_lshl_add_u64 v[110:111], v[24:25], 0, s[20:21]
	global_load_dword v90, v[110:111], off nt
	v_lshl_add_u64 v[112:113], v[22:23], 0, s[20:21]
	global_load_dword v91, v[112:113], off nt
	v_lshl_add_u64 v[114:115], v[20:21], 0, s[20:21]
	global_load_dword v92, v[114:115], off nt
	v_lshl_add_u64 v[116:117], v[18:19], 0, s[20:21]
	global_load_dword v93, v[116:117], off nt
	s_add_u32 s20, s20, 0x10000
	s_addc_u32 s21, s21, 0
	v_lshl_add_u64 v[110:111], v[32:33], 0, s[20:21]
	global_load_dword v94, v[110:111], off nt
	v_lshl_add_u64 v[112:113], v[30:31], 0, s[20:21]
	global_load_dword v95, v[112:113], off nt
	v_lshl_add_u64 v[114:115], v[28:29], 0, s[20:21]
	global_load_dword v96, v[114:115], off nt
	v_lshl_add_u64 v[116:117], v[26:27], 0, s[20:21]
	global_load_dword v97, v[116:117], off nt
	v_lshl_add_u64 v[110:111], v[24:25], 0, s[20:21]
	global_load_dword v98, v[110:111], off nt
	v_lshl_add_u64 v[112:113], v[22:23], 0, s[20:21]
	global_load_dword v99, v[112:113], off nt
	v_lshl_add_u64 v[114:115], v[20:21], 0, s[20:21]
	global_load_dword v100, v[114:115], off nt
	v_lshl_add_u64 v[116:117], v[18:19], 0, s[20:21]
	global_load_dword v101, v[116:117], off nt
	s_add_u32 s20, s20, 0x10000
	s_addc_u32 s21, s21, 0
	v_lshl_add_u64 v[110:111], v[32:33], 0, s[20:21]
	global_load_dword v102, v[110:111], off nt
	v_lshl_add_u64 v[112:113], v[30:31], 0, s[20:21]
	global_load_dword v103, v[112:113], off nt
	v_lshl_add_u64 v[114:115], v[28:29], 0, s[20:21]
	global_load_dword v104, v[114:115], off nt
	v_lshl_add_u64 v[116:117], v[26:27], 0, s[20:21]
	global_load_dword v105, v[116:117], off nt
	v_lshl_add_u64 v[110:111], v[24:25], 0, s[20:21]
	global_load_dword v106, v[110:111], off nt
	v_lshl_add_u64 v[112:113], v[22:23], 0, s[20:21]
	global_load_dword v107, v[112:113], off nt
	v_lshl_add_u64 v[114:115], v[20:21], 0, s[20:21]
	global_load_dword v108, v[114:115], off nt
	v_lshl_add_u64 v[116:117], v[18:19], 0, s[20:21]
	global_load_dword v109, v[116:117], off nt
	s_add_u32 s20, s20, 0x10000
	s_addc_u32 s21, s21, 0
	s_waitcnt vmcnt(30)
	ds_write2_b32 v35, v78, v79 offset1:66
	s_waitcnt vmcnt(28)
	ds_write2_b32 v35, v80, v81 offset0:132 offset1:198
	v_add_u32_e32 v118, 0x400, v35
	s_waitcnt vmcnt(26)
	ds_write2_b32 v118, v82, v83 offset0:8 offset1:74
	s_waitcnt vmcnt(24)
	ds_write2_b32 v118, v84, v85 offset0:140 offset1:206
	v_add_u32_e32 v35, 0x840, v35
	s_waitcnt vmcnt(22)
	ds_write2_b32 v35, v86, v87 offset1:66
	s_waitcnt vmcnt(20)
; #define LAS __attribute__((address_space(3)))
; __device__ __forceinline__ unsigned cvt_pk_bf16(float lo, float hi) { unsigned r; asm volatile("v_cvt_pk_bf16_f32 %0, %1, %2" : "=v"(r) : "v"(lo), "v"(hi)); return r; }
; #define LDS_WAIT() asm volatile("s_waitcnt lgkmcnt(0)" ::: "memory")
;     ...
;     for (int i = 0; i < 32; ++i) { const int kk = 2 * i + (lane >> 5); scr[kk * 33 + (lane & 31)] = __builtin_nontemporal_load(W + (size_t)(k0 + kk) * N + n0 + (lane & 31)); }
;     LDS_WAIT(); asm volatile("" ::: "memory");
;     const int c = lane & 7;
; #pragma unroll
;     for (int j = 0; j < 4; ++j) { const int n = (lane >> 3) + 8 * j; const LAS float* s = scr + (8 * c) * 33 + n;
;         u32x4 o; o.x = cvt_pk_bf16(s[0 * 33] * wscale, s[1 * 33] * wscale); o.y = cvt_pk_bf16(s[2 * 33] * wscale, s[3 * 33] * wscale); o.z = cvt_pk_bf16(s[4 * 33] * wscale, s[5 * 33] * wscale); o.w = cvt_pk_bf16(s[6 * 33] * wscale, s[7 * 33] * wscale);
;         __builtin_nontemporal_store(o, (u32x4*)(WT + (size_t)(drow0 + n0 + n) * K + k0 + 8 * c)); }
;     LDS_WAIT(); asm volatile("" ::: "memory");
	ds_write2_b32 v35, v88, v89 offset0:132 offset1:198
	v_add_u32_e32 v118, 0x400, v35
	s_waitcnt vmcnt(18)
	ds_write2_b32 v118, v90, v91 offset0:8 offset1:74
	s_waitcnt vmcnt(16)
	ds_write2_b32 v118, v92, v93 offset0:140 offset1:206
	v_add_u32_e32 v35, 0x840, v35
	s_waitcnt vmcnt(14)
	ds_write2_b32 v35, v94, v95 offset1:66
	s_waitcnt vmcnt(12)
	ds_write2_b32 v35, v96, v97 offset0:132 offset1:198
	v_add_u32_e32 v118, 0x400, v35
	s_waitcnt vmcnt(10)
	ds_write2_b32 v118, v98, v99 offset0:8 offset1:74
	s_waitcnt vmcnt(8)
	ds_write2_b32 v118, v100, v101 offset0:140 offset1:206
	v_add_u32_e32 v35, 0x840, v35
	s_waitcnt vmcnt(6)
	ds_write2_b32 v35, v102, v103 offset1:66
	s_waitcnt vmcnt(4)
	ds_write2_b32 v35, v104, v105 offset0:132 offset1:198
	v_add_u32_e32 v118, 0x400, v35
	s_waitcnt vmcnt(2)
	ds_write2_b32 v118, v106, v107 offset0:8 offset1:74
	s_waitcnt vmcnt(0)
	ds_write2_b32 v118, v108, v109 offset0:140 offset1:206
	v_add_u32_e32 v35, 0x840, v35
	s_waitcnt lgkmcnt(0)
	v_readlane_b32 s14, v252, 12
	v_lshlrev_b32_e32 v22, 5, v34
	v_lshlrev_b64 v[16:17], 21, v[16:17]
	v_readlane_b32 s15, v252, 13
	ds_read2_b32 v[18:19], v40 offset1:33
	v_add_u32_e32 v0, 0xffffb400, v0
	v_and_b32_e32 v26, 0x3e0, v22
	v_lshl_add_u64 v[16:17], s[14:15], 0, v[16:17]
	s_waitcnt lgkmcnt(0)
	v_cvt_pk_bf16_f32 v18, v18, v19
	ds_read2_b32 v[20:21], v40 offset0:66 offset1:99
	v_lshl_add_u64 v[16:17], v[0:1], 1, v[16:17]
	v_lshlrev_b32_e32 v0, 1, v2
	v_or_b32_e32 v27, v26, v39
	s_waitcnt lgkmcnt(0)
	v_cvt_pk_bf16_f32 v19, v20, v21
	ds_read2_b32 v[20:21], v40 offset0:132 offset1:165
	v_lshl_add_u64 v[24:25], v[16:17], 0, v[0:1]
	v_lshlrev_b32_e32 v0, 11, v27
	s_waitcnt lgkmcnt(0)
	v_cvt_pk_bf16_f32 v20, v20, v21
	ds_read2_b32 v[22:23], v40 offset0:198 offset1:231
	v_lshl_add_u64 v[16:17], v[24:25], 0, v[0:1]
	s_waitcnt lgkmcnt(0)
	v_cvt_pk_bf16_f32 v21, v22, v23
	ds_read2_b32 v[22:23], v40 offset0:8 offset1:41
	global_store_dwordx4 v[16:17], v[18:21], off nt
	s_waitcnt lgkmcnt(0)
	v_cvt_pk_bf16_f32 v16, v22, v23
	ds_read2_b32 v[18:19], v40 offset0:74 offset1:107
	v_or_b32_e32 v0, v26, v41
	s_waitcnt lgkmcnt(0)
	v_cvt_pk_bf16_f32 v17, v18, v19
	ds_read2_b32 v[18:19], v40 offset0:140 offset1:173
	v_lshlrev_b32_e32 v0, 11, v0
	s_waitcnt lgkmcnt(0)
	v_cvt_pk_bf16_f32 v18, v18, v19
	ds_read2_b32 v[20:21], v40 offset0:206 offset1:239
	s_waitcnt lgkmcnt(0)
	v_cvt_pk_bf16_f32 v19, v20, v21
	v_lshl_add_u64 v[22:23], v[24:25], 0, v[0:1]
	ds_read2_b32 v[20:21], v40 offset0:16 offset1:49
	global_store_dwordx4 v[22:23], v[16:19], off nt
	v_or_b32_e32 v0, v26, v42
	v_lshlrev_b32_e32 v0, 11, v0
	s_waitcnt lgkmcnt(0)
	v_cvt_pk_bf16_f32 v16, v20, v21
	ds_read2_b32 v[18:19], v40 offset0:82 offset1:115
	s_waitcnt lgkmcnt(0)
	v_cvt_pk_bf16_f32 v17, v18, v19
	ds_read2_b32 v[18:19], v40 offset0:148 offset1:181
	s_waitcnt lgkmcnt(0)
	v_cvt_pk_bf16_f32 v18, v18, v19
	ds_read2_b32 v[20:21], v40 offset0:214 offset1:247
	s_waitcnt lgkmcnt(0)
	v_cvt_pk_bf16_f32 v19, v20, v21
	v_lshl_add_u64 v[22:23], v[24:25], 0, v[0:1]
	ds_read2_b32 v[20:21], v40 offset0:24 offset1:57
	global_store_dwordx4 v[22:23], v[16:19], off nt
	v_or_b32_e32 v0, v26, v43
	v_lshlrev_b32_e32 v0, 11, v0
	s_waitcnt lgkmcnt(0)
	v_cvt_pk_bf16_f32 v16, v20, v21
	ds_read2_b32 v[18:19], v40 offset0:90 offset1:123
	s_waitcnt lgkmcnt(0)
	v_cvt_pk_bf16_f32 v17, v18, v19
	ds_read2_b32 v[18:19], v40 offset0:156 offset1:189
	s_waitcnt lgkmcnt(0)
	v_cvt_pk_bf16_f32 v18, v18, v19
	ds_read2_b32 v[20:21], v40 offset0:222 offset1:255
	s_waitcnt lgkmcnt(0)
	v_cvt_pk_bf16_f32 v19, v20, v21
	v_lshl_add_u64 v[20:21], v[24:25], 0, v[0:1]
	global_store_dwordx4 v[20:21], v[16:19], off nt
	s_waitcnt lgkmcnt(0)

; #define LDS_WAIT() asm volatile("s_waitcnt lgkmcnt(0)" ::: "memory")
; #pragma unroll 8
;     for (int i = 0; i < 32; ++i) { const int kk = 2 * i + (lane >> 5); scr[kk * 33 + (lane & 31)] = __builtin_nontemporal_load(W + (size_t)(k0 + kk) * N + n0 + (lane & 31)); }
;     LDS_WAIT(); asm volatile("" ::: "memory");
; __device__ __forceinline__ void prologue_a(const Args& a, LAS unsigned char* lds, int tid, int G) {
;     ...
;                 r -= 8448; const int kb = r / 80, nb = r % 80;
;                 transpose_item(a.in[I_WIN] + (size_t)l * DM * INC, INC, kb * 64, nb * 32, (bf16_t*)(ws + WS_WIN) + (size_t)l * INC * DM, DM, 0, scr, lane);
.LBB0_38:
	v_lshl_add_u64 v[110:111], v[32:33], 0, s[20:21]
	global_load_dword v78, v[110:111], off nt
	v_lshl_add_u64 v[112:113], v[30:31], 0, s[20:21]
	global_load_dword v79, v[112:113], off nt
	v_lshl_add_u64 v[114:115], v[28:29], 0, s[20:21]
	global_load_dword v80, v[114:115], off nt
	v_lshl_add_u64 v[116:117], v[26:27], 0, s[20:21]
	global_load_dword v81, v[116:117], off nt
	v_lshl_add_u64 v[110:111], v[24:25], 0, s[20:21]
	global_load_dword v82, v[110:111], off nt
	v_lshl_add_u64 v[112:113], v[22:23], 0, s[20:21]
	global_load_dword v83, v[112:113], off nt
	v_lshl_add_u64 v[114:115], v[20:21], 0, s[20:21]
	global_load_dword v84, v[114:115], off nt
	v_lshl_add_u64 v[116:117], v[18:19], 0, s[20:21]
	global_load_dword v85, v[116:117], off nt
	s_add_u32 s20, s20, 0x28000
	s_addc_u32 s21, s21, 0
	v_lshl_add_u64 v[110:111], v[32:33], 0, s[20:21]
	global_load_dword v86, v[110:111], off nt
	v_lshl_add_u64 v[112:113], v[30:31], 0, s[20:21]
	global_load_dword v87, v[112:113], off nt
	v_lshl_add_u64 v[114:115], v[28:29], 0, s[20:21]
	global_load_dword v88, v[114:115], off nt
	v_lshl_add_u64 v[116:117], v[26:27], 0, s[20:21]
	global_load_dword v89, v[116:117], off nt
	v_lshl_add_u64 v[110:111], v[24:25], 0, s[20:21]
	global_load_dword v90, v[110:111], off nt
	v_lshl_add_u64 v[112:113], v[22:23], 0, s[20:21]
	global_load_dword v91, v[112:113], off nt
	v_lshl_add_u64 v[114:115], v[20:21], 0, s[20:21]
	global_load_dword v92, v[114:115], off nt
	v_lshl_add_u64 v[116:117], v[18:19], 0, s[20:21]
	global_load_dword v93, v[116:117], off nt
	s_add_u32 s20, s20, 0x28000
	s_addc_u32 s21, s21, 0
	v_lshl_add_u64 v[110:111], v[32:33], 0, s[20:21]
	global_load_dword v94, v[110:111], off nt
	v_lshl_add_u64 v[112:113], v[30:31], 0, s[20:21]
	global_load_dword v95, v[112:113], off nt
	v_lshl_add_u64 v[114:115], v[28:29], 0, s[20:21]
	global_load_dword v96, v[114:115], off nt
	v_lshl_add_u64 v[116:117], v[26:27], 0, s[20:21]
	global_load_dword v97, v[116:117], off nt
	v_lshl_add_u64 v[110:111], v[24:25], 0, s[20:21]
	global_load_dword v98, v[110:111], off nt
	v_lshl_add_u64 v[112:113], v[22:23], 0, s[20:21]
	global_load_dword v99, v[112:113], off nt
	v_lshl_add_u64 v[114:115], v[20:21], 0, s[20:21]
	global_load_dword v100, v[114:115], off nt
	v_lshl_add_u64 v[116:117], v[18:19], 0, s[20:21]
	global_load_dword v101, v[116:117], off nt
	s_add_u32 s20, s20, 0x28000
	s_addc_u32 s21, s21, 0
	v_lshl_add_u64 v[110:111], v[32:33], 0, s[20:21]
	global_load_dword v102, v[110:111], off nt
	v_lshl_add_u64 v[112:113], v[30:31], 0, s[20:21]
	global_load_dword v103, v[112:113], off nt
	v_lshl_add_u64 v[114:115], v[28:29], 0, s[20:21]
	global_load_dword v104, v[114:115], off nt
	v_lshl_add_u64 v[116:117], v[26:27], 0, s[20:21]
	global_load_dword v105, v[116:117], off nt
	v_lshl_add_u64 v[110:111], v[24:25], 0, s[20:21]
	global_load_dword v106, v[110:111], off nt
	v_lshl_add_u64 v[112:113], v[22:23], 0, s[20:21]
	global_load_dword v107, v[112:113], off nt
	v_lshl_add_u64 v[114:115], v[20:21], 0, s[20:21]
	global_load_dword v108, v[114:115], off nt
	v_lshl_add_u64 v[116:117], v[18:19], 0, s[20:21]
	global_load_dword v109, v[116:117], off nt
	s_add_u32 s20, s20, 0x28000
	s_addc_u32 s21, s21, 0
	s_waitcnt vmcnt(30)
	ds_write2_b32 v0, v78, v79 offset1:66
	s_waitcnt vmcnt(28)
	ds_write2_b32 v0, v80, v81 offset0:132 offset1:198
	v_add_u32_e32 v118, 0x400, v0
	s_waitcnt vmcnt(26)
	ds_write2_b32 v118, v82, v83 offset0:8 offset1:74
	s_waitcnt vmcnt(24)
	ds_write2_b32 v118, v84, v85 offset0:140 offset1:206
	v_add_u32_e32 v0, 0x840, v0
	s_waitcnt vmcnt(22)
	ds_write2_b32 v0, v86, v87 offset1:66
	s_waitcnt vmcnt(20)
; #define LAS __attribute__((address_space(3)))
; __device__ __forceinline__ unsigned cvt_pk_bf16(float lo, float hi) { unsigned r; asm volatile("v_cvt_pk_bf16_f32 %0, %1, %2" : "=v"(r) : "v"(lo), "v"(hi)); return r; }
; #define LDS_WAIT() asm volatile("s_waitcnt lgkmcnt(0)" ::: "memory")
;     ...
;     for (int i = 0; i < 32; ++i) { const int kk = 2 * i + (lane >> 5); scr[kk * 33 + (lane & 31)] = __builtin_nontemporal_load(W + (size_t)(k0 + kk) * N + n0 + (lane & 31)); }
;     LDS_WAIT(); asm volatile("" ::: "memory");
;     const int c = lane & 7;
; #pragma unroll
;     for (int j = 0; j < 4; ++j) { const int n = (lane >> 3) + 8 * j; const LAS float* s = scr + (8 * c) * 33 + n;
;         u32x4 o; o.x = cvt_pk_bf16(s[0 * 33] * wscale, s[1 * 33] * wscale); o.y = cvt_pk_bf16(s[2 * 33] * wscale, s[3 * 33] * wscale); o.z = cvt_pk_bf16(s[4 * 33] * wscale, s[5 * 33] * wscale); o.w = cvt_pk_bf16(s[6 * 33] * wscale, s[7 * 33] * wscale);
;         __builtin_nontemporal_store(o, (u32x4*)(WT + (size_t)(drow0 + n0 + n) * K + k0 + 8 * c)); }
;     LDS_WAIT(); asm volatile("" ::: "memory");
	ds_write2_b32 v0, v88, v89 offset0:132 offset1:198
	v_add_u32_e32 v118, 0x400, v0
	s_waitcnt vmcnt(18)
	ds_write2_b32 v118, v90, v91 offset0:8 offset1:74
	s_waitcnt vmcnt(16)
	ds_write2_b32 v118, v92, v93 offset0:140 offset1:206
	v_add_u32_e32 v0, 0x840, v0
	s_waitcnt vmcnt(14)
	ds_write2_b32 v0, v94, v95 offset1:66
	s_waitcnt vmcnt(12)
	ds_write2_b32 v0, v96, v97 offset0:132 offset1:198
	v_add_u32_e32 v118, 0x400, v0
	s_waitcnt vmcnt(10)
	ds_write2_b32 v118, v98, v99 offset0:8 offset1:74
	s_waitcnt vmcnt(8)
	ds_write2_b32 v118, v100, v101 offset0:140 offset1:206
	v_add_u32_e32 v0, 0x840, v0
	s_waitcnt vmcnt(6)
	ds_write2_b32 v0, v102, v103 offset1:66
	s_waitcnt vmcnt(4)
	ds_write2_b32 v0, v104, v105 offset0:132 offset1:198
	v_add_u32_e32 v118, 0x400, v0
	s_waitcnt vmcnt(2)
	ds_write2_b32 v118, v106, v107 offset0:8 offset1:74
	s_waitcnt vmcnt(0)
	ds_write2_b32 v118, v108, v109 offset0:140 offset1:206
	v_add_u32_e32 v0, 0x840, v0
	s_waitcnt lgkmcnt(0)
	v_readlane_b32 s14, v252, 14
	v_mul_hi_i32_i24_e32 v23, 0x500000, v16
	v_mul_i32_i24_e32 v22, 0x500000, v16
	v_readlane_b32 s15, v252, 15
	ds_read2_b32 v[18:19], v40 offset1:33
	v_lshlrev_b32_sdwa v0, v188, v34 dst_sel:DWORD dst_unused:UNUSED_PAD src0_sel:DWORD src1_sel:WORD_0
	v_lshl_add_u64 v[22:23], s[14:15], 0, v[22:23]
	s_waitcnt lgkmcnt(0)
	v_cvt_pk_bf16_f32 v18, v18, v19
	ds_read2_b32 v[20:21], v40 offset0:66 offset1:99
	v_or_b32_e32 v16, v39, v17
	v_lshl_add_u64 v[22:23], v[22:23], 0, v[0:1]
	v_lshlrev_b32_e32 v0, 1, v2
	s_waitcnt lgkmcnt(0)
	v_cvt_pk_bf16_f32 v19, v20, v21
	ds_read2_b32 v[20:21], v40 offset0:132 offset1:165
	v_lshl_add_u64 v[22:23], v[22:23], 0, v[0:1]
	v_lshlrev_b32_e32 v0, 11, v16
	s_waitcnt lgkmcnt(0)
	v_cvt_pk_bf16_f32 v20, v20, v21
	ds_read2_b32 v[24:25], v40 offset0:198 offset1:231
	s_waitcnt lgkmcnt(0)
	v_cvt_pk_bf16_f32 v21, v24, v25
	v_lshl_add_u64 v[26:27], v[22:23], 0, v[0:1]
	ds_read2_b32 v[24:25], v40 offset0:8 offset1:41
	global_store_dwordx4 v[26:27], v[18:21], off nt
	v_or_b32_e32 v0, v41, v17
	v_lshlrev_b32_e32 v0, 11, v0
	s_waitcnt lgkmcnt(0)
	v_cvt_pk_bf16_f32 v18, v24, v25
	ds_read2_b32 v[20:21], v40 offset0:74 offset1:107
	s_waitcnt lgkmcnt(0)
	v_cvt_pk_bf16_f32 v19, v20, v21
	ds_read2_b32 v[20:21], v40 offset0:140 offset1:173
	s_waitcnt lgkmcnt(0)
	v_cvt_pk_bf16_f32 v20, v20, v21
	ds_read2_b32 v[24:25], v40 offset0:206 offset1:239
	s_waitcnt lgkmcnt(0)
	v_cvt_pk_bf16_f32 v21, v24, v25
	v_lshl_add_u64 v[26:27], v[22:23], 0, v[0:1]
	ds_read2_b32 v[24:25], v40 offset0:16 offset1:49
	global_store_dwordx4 v[26:27], v[18:21], off nt
	v_or_b32_e32 v0, v42, v17
	v_lshlrev_b32_e32 v0, 11, v0
	s_waitcnt lgkmcnt(0)
	v_cvt_pk_bf16_f32 v18, v24, v25
	ds_read2_b32 v[20:21], v40 offset0:82 offset1:115
	s_waitcnt lgkmcnt(0)
	v_cvt_pk_bf16_f32 v19, v20, v21
	ds_read2_b32 v[20:21], v40 offset0:148 offset1:181
	s_waitcnt lgkmcnt(0)
	v_cvt_pk_bf16_f32 v20, v20, v21
	ds_read2_b32 v[24:25], v40 offset0:214 offset1:247
	s_waitcnt lgkmcnt(0)
	v_cvt_pk_bf16_f32 v21, v24, v25
	v_lshl_add_u64 v[26:27], v[22:23], 0, v[0:1]
	v_or_b32_e32 v0, v43, v17
	ds_read2_b32 v[24:25], v40 offset0:24 offset1:57
	global_store_dwordx4 v[26:27], v[18:21], off nt
	v_lshlrev_b32_e32 v0, 11, v0
	v_lshl_add_u64 v[16:17], v[22:23], 0, v[0:1]
	s_waitcnt lgkmcnt(0)
	v_cvt_pk_bf16_f32 v18, v24, v25
	ds_read2_b32 v[20:21], v40 offset0:90 offset1:123
	s_waitcnt lgkmcnt(0)
	v_cvt_pk_bf16_f32 v19, v20, v21
	ds_read2_b32 v[20:21], v40 offset0:156 offset1:189
	s_waitcnt lgkmcnt(0)
	v_cvt_pk_bf16_f32 v20, v20, v21
	ds_read2_b32 v[24:25], v40 offset0:222 offset1:255
	s_waitcnt lgkmcnt(0)
	v_cvt_pk_bf16_f32 v21, v24, v25
	global_store_dwordx4 v[16:17], v[18:21], off nt
	s_waitcnt lgkmcnt(0)

; #define LDS_WAIT() asm volatile("s_waitcnt lgkmcnt(0)" ::: "memory")
; #pragma unroll 8
;     for (int i = 0; i < 32; ++i) { const int kk = 2 * i + (lane >> 5); scr[kk * 33 + (lane & 31)] = __builtin_nontemporal_load(W + (size_t)(k0 + kk) * N + n0 + (lane & 31)); }
;     LDS_WAIT(); asm volatile("" ::: "memory");
; __device__ __forceinline__ void prologue_a(const Args& a, LAS unsigned char* lds, int tid, int G) {
;     ...
;                 r -= 5632; const int sub = r / 1408, rr = r % 1408, kb = rr / 32, nb = rr % 32;
;                 const float* W = a.in[I_WD] + (size_t)(l * 2 + sub) * DFF * DM;
;                 bf16_t* WT = (bf16_t*)(ws + WS_WD) + (size_t)(l * 2 + sub) * DM * DFF;
;                 transpose_item(W, DM, kb * 64, nb * 32, WT, DFF, 0, scr, lane);
.LBB0_43:
	v_lshl_add_u64 v[110:111], v[24:25], 0, s[18:19]
	global_load_dword v78, v[110:111], off nt
	v_add_co_u32_e32 v112, vcc, 0x2000, v110
	s_nop 1
	v_addc_co_u32_e32 v113, vcc, 0, v111, vcc
	global_load_dword v79, v[112:113], off nt
	v_add_co_u32_e32 v114, vcc, 0x4000, v110
	s_nop 1
	v_addc_co_u32_e32 v115, vcc, 0, v111, vcc
	global_load_dword v80, v[114:115], off nt
	v_add_co_u32_e32 v116, vcc, 0x6000, v110
	s_nop 1
	v_addc_co_u32_e32 v117, vcc, 0, v111, vcc
	global_load_dword v81, v[116:117], off nt
	v_lshl_add_u64 v[110:111], v[22:23], 0, s[18:19]
	global_load_dword v82, v[110:111], off nt
	v_lshl_add_u64 v[112:113], v[20:21], 0, s[18:19]
	global_load_dword v83, v[112:113], off nt
	v_lshl_add_u64 v[114:115], v[18:19], 0, s[18:19]
	global_load_dword v84, v[114:115], off nt
	v_lshl_add_u64 v[116:117], v[16:17], 0, s[18:19]
	global_load_dword v85, v[116:117], off nt
	s_add_u32 s18, s18, 0x10000
	s_addc_u32 s19, s19, 0
	v_lshl_add_u64 v[110:111], v[24:25], 0, s[18:19]
	global_load_dword v86, v[110:111], off nt
	v_add_co_u32_e32 v112, vcc, 0x2000, v110
	s_nop 1
	v_addc_co_u32_e32 v113, vcc, 0, v111, vcc
	global_load_dword v87, v[112:113], off nt
	v_add_co_u32_e32 v114, vcc, 0x4000, v110
	s_nop 1
	v_addc_co_u32_e32 v115, vcc, 0, v111, vcc
	global_load_dword v88, v[114:115], off nt
	v_add_co_u32_e32 v116, vcc, 0x6000, v110
	s_nop 1
	v_addc_co_u32_e32 v117, vcc, 0, v111, vcc
	global_load_dword v89, v[116:117], off nt
	v_lshl_add_u64 v[110:111], v[22:23], 0, s[18:19]
	global_load_dword v90, v[110:111], off nt
	v_lshl_add_u64 v[112:113], v[20:21], 0, s[18:19]
	global_load_dword v91, v[112:113], off nt
	v_lshl_add_u64 v[114:115], v[18:19], 0, s[18:19]
	global_load_dword v92, v[114:115], off nt
	v_lshl_add_u64 v[116:117], v[16:17], 0, s[18:19]
	global_load_dword v93, v[116:117], off nt
	s_add_u32 s18, s18, 0x10000
	s_addc_u32 s19, s19, 0
	v_lshl_add_u64 v[110:111], v[24:25], 0, s[18:19]
	global_load_dword v94, v[110:111], off nt
	v_add_co_u32_e32 v112, vcc, 0x2000, v110
	s_nop 1
	v_addc_co_u32_e32 v113, vcc, 0, v111, vcc
	global_load_dword v95, v[112:113], off nt
	v_add_co_u32_e32 v114, vcc, 0x4000, v110
	s_nop 1
	v_addc_co_u32_e32 v115, vcc, 0, v111, vcc
	global_load_dword v96, v[114:115], off nt
	v_add_co_u32_e32 v116, vcc, 0x6000, v110
	s_nop 1
	v_addc_co_u32_e32 v117, vcc, 0, v111, vcc
	global_load_dword v97, v[116:117], off nt
	v_lshl_add_u64 v[110:111], v[22:23], 0, s[18:19]
	global_load_dword v98, v[110:111], off nt
	v_lshl_add_u64 v[112:113], v[20:21], 0, s[18:19]
	global_load_dword v99, v[112:113], off nt
	v_lshl_add_u64 v[114:115], v[18:19], 0, s[18:19]
	global_load_dword v100, v[114:115], off nt
	v_lshl_add_u64 v[116:117], v[16:17], 0, s[18:19]
	global_load_dword v101, v[116:117], off nt
	s_add_u32 s18, s18, 0x10000
	s_addc_u32 s19, s19, 0
	v_lshl_add_u64 v[110:111], v[24:25], 0, s[18:19]
	global_load_dword v102, v[110:111], off nt
	v_add_co_u32_e32 v112, vcc, 0x2000, v110
	s_nop 1
	v_addc_co_u32_e32 v113, vcc, 0, v111, vcc
	global_load_dword v103, v[112:113], off nt
	v_add_co_u32_e32 v114, vcc, 0x4000, v110
	s_nop 1
	v_addc_co_u32_e32 v115, vcc, 0, v111, vcc
	global_load_dword v104, v[114:115], off nt
	v_add_co_u32_e32 v116, vcc, 0x6000, v110
	s_nop 1
	v_addc_co_u32_e32 v117, vcc, 0, v111, vcc
	global_load_dword v105, v[116:117], off nt
	v_lshl_add_u64 v[110:111], v[22:23], 0, s[18:19]
	global_load_dword v106, v[110:111], off nt
	v_lshl_add_u64 v[112:113], v[20:21], 0, s[18:19]
	global_load_dword v107, v[112:113], off nt
	v_lshl_add_u64 v[114:115], v[18:19], 0, s[18:19]
	global_load_dword v108, v[114:115], off nt
	v_lshl_add_u64 v[116:117], v[16:17], 0, s[18:19]
	global_load_dword v109, v[116:117], off nt
	s_add_u32 s18, s18, 0x10000
	s_addc_u32 s19, s19, 0
	s_waitcnt vmcnt(30)
	ds_write2_b32 v0, v78, v79 offset1:66
	s_waitcnt vmcnt(28)
	ds_write2_b32 v0, v80, v81 offset0:132 offset1:198
	v_add_u32_e32 v118, 0x400, v0
	s_waitcnt vmcnt(26)
; #define LAS __attribute__((address_space(3)))
; __device__ __forceinline__ unsigned cvt_pk_bf16(float lo, float hi) { unsigned r; asm volatile("v_cvt_pk_bf16_f32 %0, %1, %2" : "=v"(r) : "v"(lo), "v"(hi)); return r; }
; #define LDS_WAIT() asm volatile("s_waitcnt lgkmcnt(0)" ::: "memory")
;     ...
;     for (int i = 0; i < 32; ++i) { const int kk = 2 * i + (lane >> 5); scr[kk * 33 + (lane & 31)] = __builtin_nontemporal_load(W + (size_t)(k0 + kk) * N + n0 + (lane & 31)); }
;     LDS_WAIT(); asm volatile("" ::: "memory");
;     const int c = lane & 7;
; #pragma unroll
;     for (int j = 0; j < 4; ++j) { const int n = (lane >> 3) + 8 * j; const LAS float* s = scr + (8 * c) * 33 + n;
;         u32x4 o; o.x = cvt_pk_bf16(s[0 * 33] * wscale, s[1 * 33] * wscale); o.y = cvt_pk_bf16(s[2 * 33] * wscale, s[3 * 33] * wscale); o.z = cvt_pk_bf16(s[4 * 33] * wscale, s[5 * 33] * wscale); o.w = cvt_pk_bf16(s[6 * 33] * wscale, s[7 * 33] * wscale);
;         __builtin_nontemporal_store(o, (u32x4*)(WT + (size_t)(drow0 + n0 + n) * K + k0 + 8 * c)); }
;     LDS_WAIT(); asm volatile("" ::: "memory");
	ds_write2_b32 v118, v82, v83 offset0:8 offset1:74
	s_waitcnt vmcnt(24)
	ds_write2_b32 v118, v84, v85 offset0:140 offset1:206
	v_add_u32_e32 v0, 0x840, v0
	s_waitcnt vmcnt(22)
	ds_write2_b32 v0, v86, v87 offset1:66
	s_waitcnt vmcnt(20)
	ds_write2_b32 v0, v88, v89 offset0:132 offset1:198
	v_add_u32_e32 v118, 0x400, v0
	s_waitcnt vmcnt(18)
	ds_write2_b32 v118, v90, v91 offset0:8 offset1:74
	s_waitcnt vmcnt(16)
	ds_write2_b32 v118, v92, v93 offset0:140 offset1:206
	v_add_u32_e32 v0, 0x840, v0
	s_waitcnt vmcnt(14)
	ds_write2_b32 v0, v94, v95 offset1:66
	s_waitcnt vmcnt(12)
	ds_write2_b32 v0, v96, v97 offset0:132 offset1:198
	v_add_u32_e32 v118, 0x400, v0
	s_waitcnt vmcnt(10)
	ds_write2_b32 v118, v98, v99 offset0:8 offset1:74
	s_waitcnt vmcnt(8)
	ds_write2_b32 v118, v100, v101 offset0:140 offset1:206
	v_add_u32_e32 v0, 0x840, v0
	s_waitcnt vmcnt(6)
	ds_write2_b32 v0, v102, v103 offset1:66
	s_waitcnt vmcnt(4)
	ds_write2_b32 v0, v104, v105 offset0:132 offset1:198
	v_add_u32_e32 v118, 0x400, v0
	s_waitcnt vmcnt(2)
	ds_write2_b32 v118, v106, v107 offset0:8 offset1:74
	s_waitcnt vmcnt(0)
	ds_write2_b32 v118, v108, v109 offset0:140 offset1:206
	v_add_u32_e32 v0, 0x840, v0
	v_lshlrev_b32_e32 v22, 5, v28
	v_mul_hi_i32_i24_e32 v21, 0x580000, v26
	v_mul_i32_i24_e32 v20, 0x580000, v26
	s_waitcnt lgkmcnt(0)
	v_lshlrev_b32_e32 v0, 1, v27
	v_and_b32_e32 v26, 0x3e0, v22
	v_lshl_add_u64 v[20:21], s[22:23], 0, v[20:21]
	v_lshl_add_u64 v[20:21], v[20:21], 0, v[0:1]
	v_lshlrev_b32_e32 v0, 1, v2
	v_or_b32_e32 v24, v26, v39
	ds_read2_b32 v[16:17], v40 offset1:33
	v_lshl_add_u64 v[20:21], v[20:21], 0, v[0:1]
	v_mul_u32_u24_e32 v0, 0xb00, v24
	s_waitcnt lgkmcnt(0)
	v_cvt_pk_bf16_f32 v16, v16, v17
	ds_read2_b32 v[18:19], v40 offset0:66 offset1:99
	v_lshlrev_b32_e32 v0, 1, v0
	s_waitcnt lgkmcnt(0)
	v_cvt_pk_bf16_f32 v17, v18, v19
	ds_read2_b32 v[18:19], v40 offset0:132 offset1:165
	v_lshl_add_u64 v[24:25], v[20:21], 0, v[0:1]
	v_or_b32_e32 v0, v26, v41
	s_waitcnt lgkmcnt(0)
	v_cvt_pk_bf16_f32 v18, v18, v19
	ds_read2_b32 v[22:23], v40 offset0:198 offset1:231
	s_waitcnt lgkmcnt(0)
	v_cvt_pk_bf16_f32 v19, v22, v23
	v_mul_u32_u24_e32 v0, 0xb00, v0
	ds_read2_b32 v[22:23], v40 offset0:8 offset1:41
	global_store_dwordx4 v[24:25], v[16:19], off nt
	v_lshlrev_b32_e32 v0, 1, v0
	v_lshl_add_u64 v[24:25], v[20:21], 0, v[0:1]
	s_waitcnt lgkmcnt(0)
	v_cvt_pk_bf16_f32 v16, v22, v23
	ds_read2_b32 v[18:19], v40 offset0:74 offset1:107
	s_waitcnt lgkmcnt(0)
	v_cvt_pk_bf16_f32 v17, v18, v19
	ds_read2_b32 v[18:19], v40 offset0:140 offset1:173
	v_or_b32_e32 v0, v26, v42
	s_waitcnt lgkmcnt(0)
	v_cvt_pk_bf16_f32 v18, v18, v19
	ds_read2_b32 v[22:23], v40 offset0:206 offset1:239
	s_waitcnt lgkmcnt(0)
	v_cvt_pk_bf16_f32 v19, v22, v23
	v_mul_u32_u24_e32 v0, 0xb00, v0
	ds_read2_b32 v[22:23], v40 offset0:16 offset1:49
	global_store_dwordx4 v[24:25], v[16:19], off nt
	v_lshlrev_b32_e32 v0, 1, v0
	v_lshl_add_u64 v[24:25], v[20:21], 0, v[0:1]
	s_waitcnt lgkmcnt(0)
	v_cvt_pk_bf16_f32 v16, v22, v23
	ds_read2_b32 v[18:19], v40 offset0:82 offset1:115
	s_waitcnt lgkmcnt(0)
	v_cvt_pk_bf16_f32 v17, v18, v19
	ds_read2_b32 v[18:19], v40 offset0:148 offset1:181
	v_or_b32_e32 v0, v26, v43
	s_waitcnt lgkmcnt(0)
	v_cvt_pk_bf16_f32 v18, v18, v19
	ds_read2_b32 v[22:23], v40 offset0:214 offset1:247
	s_waitcnt lgkmcnt(0)
	v_cvt_pk_bf16_f32 v19, v22, v23
	v_mul_u32_u24_e32 v0, 0xb00, v0
	ds_read2_b32 v[22:23], v40 offset0:24 offset1:57
	global_store_dwordx4 v[24:25], v[16:19], off nt
	v_lshlrev_b32_e32 v0, 1, v0
	v_lshl_add_u64 v[20:21], v[20:21], 0, v[0:1]
	s_waitcnt lgkmcnt(0)
	v_cvt_pk_bf16_f32 v16, v22, v23
	ds_read2_b32 v[18:19], v40 offset0:90 offset1:123
	s_waitcnt lgkmcnt(0)
	v_cvt_pk_bf16_f32 v17, v18, v19
	ds_read2_b32 v[18:19], v40 offset0:156 offset1:189
	s_waitcnt lgkmcnt(0)
	v_cvt_pk_bf16_f32 v18, v18, v19
	ds_read2_b32 v[22:23], v40 offset0:222 offset1:255
	s_waitcnt lgkmcnt(0)
	v_cvt_pk_bf16_f32 v19, v22, v23
	global_store_dwordx4 v[20:21], v[16:19], off nt
	s_waitcnt lgkmcnt(0)

; #define LDS_WAIT() asm volatile("s_waitcnt lgkmcnt(0)" ::: "memory")
; #pragma unroll 8
;     for (int i = 0; i < 32; ++i) { const int kk = 2 * i + (lane >> 5); scr[kk * 33 + (lane & 31)] = __builtin_nontemporal_load(W + (size_t)(k0 + kk) * N + n0 + (lane & 31)); }
;     LDS_WAIT(); asm volatile("" ::: "memory");
; __device__ __forceinline__ void prologue_a(const Args& a, LAS unsigned char* lds, int tid, int G) {
;     ...
;                 const int up = r >= 2816; if (up) r -= 2816;
;                 const int sub = r / 1408, rr = r % 1408, kb = rr / 88, nb = rr % 88, n0 = nb * 32;
;                 const float* W = a.in[up ? I_WU : I_WG] + (size_t)(l * 2 + sub) * DM * DFF;
;                 bf16_t* WT = (bf16_t*)(ws + WS_WGU) + (size_t)(l * 2 + sub) * NGU * DM;
;                 transpose_item(W, DFF, kb * 64, n0, WT, DM, 256 * (n0 >> 7) + (up ? 128 : 0) + (n0 & 127) - n0, scr, lane, up ? (1.0f / LOG2E) : LOG2E);
.LBB0_50:
	v_lshl_add_u64 v[110:111], v[36:37], 0, s[12:13]
	global_load_dword v78, v[110:111], off nt
	v_lshl_add_u64 v[112:113], v[34:35], 0, s[12:13]
	global_load_dword v79, v[112:113], off nt
	v_lshl_add_u64 v[114:115], v[32:33], 0, s[12:13]
	global_load_dword v80, v[114:115], off nt
	v_lshl_add_u64 v[116:117], v[30:31], 0, s[12:13]
	global_load_dword v81, v[116:117], off nt
	v_lshl_add_u64 v[110:111], v[28:29], 0, s[12:13]
	global_load_dword v82, v[110:111], off nt
	v_lshl_add_u64 v[112:113], v[26:27], 0, s[12:13]
	global_load_dword v83, v[112:113], off nt
	v_lshl_add_u64 v[114:115], v[24:25], 0, s[12:13]
	global_load_dword v84, v[114:115], off nt
	v_lshl_add_u64 v[116:117], v[22:23], 0, s[12:13]
	global_load_dword v85, v[116:117], off nt
	s_add_u32 s12, s12, 0x2c000
	s_addc_u32 s13, s13, 0
	v_lshl_add_u64 v[110:111], v[36:37], 0, s[12:13]
	global_load_dword v86, v[110:111], off nt
	v_lshl_add_u64 v[112:113], v[34:35], 0, s[12:13]
	global_load_dword v87, v[112:113], off nt
	v_lshl_add_u64 v[114:115], v[32:33], 0, s[12:13]
	global_load_dword v88, v[114:115], off nt
	v_lshl_add_u64 v[116:117], v[30:31], 0, s[12:13]
	global_load_dword v89, v[116:117], off nt
	v_lshl_add_u64 v[110:111], v[28:29], 0, s[12:13]
	global_load_dword v90, v[110:111], off nt
	v_lshl_add_u64 v[112:113], v[26:27], 0, s[12:13]
	global_load_dword v91, v[112:113], off nt
	v_lshl_add_u64 v[114:115], v[24:25], 0, s[12:13]
	global_load_dword v92, v[114:115], off nt
	v_lshl_add_u64 v[116:117], v[22:23], 0, s[12:13]
	global_load_dword v93, v[116:117], off nt
	s_add_u32 s12, s12, 0x2c000
	s_addc_u32 s13, s13, 0
	v_lshl_add_u64 v[110:111], v[36:37], 0, s[12:13]
	global_load_dword v94, v[110:111], off nt
	v_lshl_add_u64 v[112:113], v[34:35], 0, s[12:13]
	global_load_dword v95, v[112:113], off nt
	v_lshl_add_u64 v[114:115], v[32:33], 0, s[12:13]
	global_load_dword v96, v[114:115], off nt
	v_lshl_add_u64 v[116:117], v[30:31], 0, s[12:13]
	global_load_dword v97, v[116:117], off nt
	v_lshl_add_u64 v[110:111], v[28:29], 0, s[12:13]
	global_load_dword v98, v[110:111], off nt
	v_lshl_add_u64 v[112:113], v[26:27], 0, s[12:13]
	global_load_dword v99, v[112:113], off nt
	v_lshl_add_u64 v[114:115], v[24:25], 0, s[12:13]
	global_load_dword v100, v[114:115], off nt
	v_lshl_add_u64 v[116:117], v[22:23], 0, s[12:13]
	global_load_dword v101, v[116:117], off nt
	s_add_u32 s12, s12, 0x2c000
	s_addc_u32 s13, s13, 0
	v_lshl_add_u64 v[110:111], v[36:37], 0, s[12:13]
	global_load_dword v102, v[110:111], off nt
	v_lshl_add_u64 v[112:113], v[34:35], 0, s[12:13]
	global_load_dword v103, v[112:113], off nt
	v_lshl_add_u64 v[114:115], v[32:33], 0, s[12:13]
	global_load_dword v104, v[114:115], off nt
	v_lshl_add_u64 v[116:117], v[30:31], 0, s[12:13]
	global_load_dword v105, v[116:117], off nt
	v_lshl_add_u64 v[110:111], v[28:29], 0, s[12:13]
	global_load_dword v106, v[110:111], off nt
	v_lshl_add_u64 v[112:113], v[26:27], 0, s[12:13]
	global_load_dword v107, v[112:113], off nt
	v_lshl_add_u64 v[114:115], v[24:25], 0, s[12:13]
	global_load_dword v108, v[114:115], off nt
	v_lshl_add_u64 v[116:117], v[22:23], 0, s[12:13]
	global_load_dword v109, v[116:117], off nt
	s_add_u32 s12, s12, 0x2c000
	s_addc_u32 s13, s13, 0
	s_waitcnt vmcnt(30)
	ds_write2_b32 v19, v78, v79 offset1:66
	s_waitcnt vmcnt(28)
	ds_write2_b32 v19, v80, v81 offset0:132 offset1:198
	v_add_u32_e32 v118, 0x400, v19
	s_waitcnt vmcnt(26)
	ds_write2_b32 v118, v82, v83 offset0:8 offset1:74
	s_waitcnt vmcnt(24)
	ds_write2_b32 v118, v84, v85 offset0:140 offset1:206
	v_add_u32_e32 v19, 0x840, v19
	s_waitcnt vmcnt(22)
	ds_write2_b32 v19, v86, v87 offset1:66
	s_waitcnt vmcnt(20)
	ds_write2_b32 v19, v88, v89 offset0:132 offset1:198
	v_add_u32_e32 v118, 0x400, v19
	s_waitcnt vmcnt(18)
	ds_write2_b32 v118, v90, v91 offset0:8 offset1:74
	s_waitcnt vmcnt(16)
	ds_write2_b32 v118, v92, v93 offset0:140 offset1:206
	v_add_u32_e32 v19, 0x840, v19
	s_waitcnt vmcnt(14)
	ds_write2_b32 v19, v94, v95 offset1:66
	s_waitcnt vmcnt(12)
	ds_write2_b32 v19, v96, v97 offset0:132 offset1:198
	v_add_u32_e32 v118, 0x400, v19
	s_waitcnt vmcnt(10)
	ds_write2_b32 v118, v98, v99 offset0:8 offset1:74
	s_waitcnt vmcnt(8)
; #define LAS __attribute__((address_space(3)))
; __device__ __forceinline__ unsigned cvt_pk_bf16(float lo, float hi) { unsigned r; asm volatile("v_cvt_pk_bf16_f32 %0, %1, %2" : "=v"(r) : "v"(lo), "v"(hi)); return r; }
; #define LDS_WAIT() asm volatile("s_waitcnt lgkmcnt(0)" ::: "memory")
;     ...
;     for (int i = 0; i < 32; ++i) { const int kk = 2 * i + (lane >> 5); scr[kk * 33 + (lane & 31)] = __builtin_nontemporal_load(W + (size_t)(k0 + kk) * N + n0 + (lane & 31)); }
;     LDS_WAIT(); asm volatile("" ::: "memory");
;     const int c = lane & 7;
; #pragma unroll
;     for (int j = 0; j < 4; ++j) { const int n = (lane >> 3) + 8 * j; const LAS float* s = scr + (8 * c) * 33 + n;
;         u32x4 o; o.x = cvt_pk_bf16(s[0 * 33] * wscale, s[1 * 33] * wscale); o.y = cvt_pk_bf16(s[2 * 33] * wscale, s[3 * 33] * wscale); o.z = cvt_pk_bf16(s[4 * 33] * wscale, s[5 * 33] * wscale); o.w = cvt_pk_bf16(s[6 * 33] * wscale, s[7 * 33] * wscale);
;         __builtin_nontemporal_store(o, (u32x4*)(WT + (size_t)(drow0 + n0 + n) * K + k0 + 8 * c)); }
;     LDS_WAIT(); asm volatile("" ::: "memory");
; __device__ __forceinline__ void prologue_a(const Args& a, LAS unsigned char* lds, int tid, int G) {
;     ...
;                 const int up = r >= 2816; if (up) r -= 2816;
;                 const int sub = r / 1408, rr = r % 1408, kb = rr / 88, nb = rr % 88, n0 = nb * 32;
;                 const float* W = a.in[up ? I_WU : I_WG] + (size_t)(l * 2 + sub) * DM * DFF;
;                 bf16_t* WT = (bf16_t*)(ws + WS_WGU) + (size_t)(l * 2 + sub) * NGU * DM;
;                 transpose_item(W, DFF, kb * 64, n0, WT, DM, 256 * (n0 >> 7) + (up ? 128 : 0) + (n0 & 127) - n0, scr, lane, up ? (1.0f / LOG2E) : LOG2E);
	ds_write2_b32 v118, v100, v101 offset0:140 offset1:206
	v_add_u32_e32 v19, 0x840, v19
	s_waitcnt vmcnt(6)
	ds_write2_b32 v19, v102, v103 offset1:66
	s_waitcnt vmcnt(4)
	ds_write2_b32 v19, v104, v105 offset0:132 offset1:198
	v_add_u32_e32 v118, 0x400, v19
	s_waitcnt vmcnt(2)
	ds_write2_b32 v118, v106, v107 offset0:8 offset1:74
	s_waitcnt vmcnt(0)
	ds_write2_b32 v118, v108, v109 offset0:140 offset1:206
	v_add_u32_e32 v19, 0x840, v19
	s_waitcnt lgkmcnt(0)
	ds_read2_b32 v[22:23], v40 offset1:33
	v_lshlrev_b32_sdwa v26, v200, sext(v0) dst_sel:DWORD dst_unused:UNUSED_PAD src0_sel:DWORD src1_sel:WORD_0
	v_and_b32_e32 v27, 0x60, v18
	v_and_b32_e32 v26, 0xffffff00, v26
	v_or3_b32 v28, v26, v61, v27
	s_waitcnt lgkmcnt(0)
	v_mul_f32_e32 v19, v60, v22
	v_mul_f32_e32 v22, v60, v23
	v_cvt_pk_bf16_f32 v22, v19, v22
	ds_read2_b32 v[24:25], v40 offset0:66 offset1:99
	s_waitcnt lgkmcnt(0)
	v_mul_f32_e32 v0, v60, v24
	v_mul_f32_e32 v19, v60, v25
	v_cvt_pk_bf16_f32 v23, v0, v19
	ds_read2_b32 v[24:25], v40 offset0:132 offset1:165
	v_lshl_add_u64 v[18:19], s[24:25], 0, v[20:21]
	v_lshlrev_b32_e32 v0, 1, v2
	v_lshl_add_u64 v[16:17], v[16:17], 1, v[18:19]
	v_lshl_add_u64 v[26:27], v[16:17], 0, v[0:1]
	s_waitcnt lgkmcnt(0)
	v_mul_f32_e32 v20, v60, v24
	v_mul_f32_e32 v21, v60, v25
	v_cvt_pk_bf16_f32 v24, v20, v21
	ds_read2_b32 v[20:21], v40 offset0:198 offset1:231
	v_or_b32_e32 v16, v28, v39
	s_waitcnt lgkmcnt(0)
	v_mul_f32_e32 v0, v60, v20
	v_mul_f32_e32 v17, v60, v21
	v_cvt_pk_bf16_f32 v25, v0, v17
	ds_read2_b32 v[18:19], v40 offset0:8 offset1:41
	v_ashrrev_i32_e32 v17, 31, v16
	v_lshlrev_b64 v[16:17], 11, v[16:17]
	v_lshl_add_u64 v[16:17], v[26:27], 0, v[16:17]
	global_store_dwordx4 v[16:17], v[22:25], off nt
	s_waitcnt lgkmcnt(0)
	v_mul_f32_e32 v16, v60, v19
	v_mul_f32_e32 v0, v60, v18
	v_cvt_pk_bf16_f32 v16, v0, v16
	ds_read2_b32 v[18:19], v40 offset0:74 offset1:107
	v_or_b32_e32 v22, v28, v41
	v_ashrrev_i32_e32 v23, 31, v22
	v_lshlrev_b64 v[22:23], 11, v[22:23]
	v_lshl_add_u64 v[22:23], v[26:27], 0, v[22:23]
	s_waitcnt lgkmcnt(0)
	v_mul_f32_e32 v17, v60, v19
	v_mul_f32_e32 v0, v60, v18
	v_cvt_pk_bf16_f32 v17, v0, v17
	ds_read2_b32 v[18:19], v40 offset0:140 offset1:173
	s_waitcnt lgkmcnt(0)
	v_mul_f32_e32 v0, v60, v18
	v_mul_f32_e32 v18, v60, v19
	v_cvt_pk_bf16_f32 v18, v0, v18
	ds_read2_b32 v[20:21], v40 offset0:206 offset1:239
	s_waitcnt lgkmcnt(0)
	v_mul_f32_e32 v19, v60, v21
	v_mul_f32_e32 v0, v60, v20
	v_cvt_pk_bf16_f32 v19, v0, v19
	ds_read2_b32 v[20:21], v40 offset0:16 offset1:49
	global_store_dwordx4 v[22:23], v[16:19], off nt
	v_or_b32_e32 v22, v28, v42
	v_ashrrev_i32_e32 v23, 31, v22
	v_lshlrev_b64 v[22:23], 11, v[22:23]
	s_waitcnt lgkmcnt(0)
	v_mul_f32_e32 v16, v60, v21
	v_mul_f32_e32 v0, v60, v20
	v_cvt_pk_bf16_f32 v16, v0, v16
	ds_read2_b32 v[18:19], v40 offset0:82 offset1:115
	v_lshl_add_u64 v[22:23], v[26:27], 0, v[22:23]
	s_waitcnt lgkmcnt(0)
	v_mul_f32_e32 v17, v60, v19
	v_mul_f32_e32 v0, v60, v18
	v_cvt_pk_bf16_f32 v17, v0, v17
	ds_read2_b32 v[18:19], v40 offset0:148 offset1:181
	s_waitcnt lgkmcnt(0)
	v_mul_f32_e32 v0, v60, v18
	v_mul_f32_e32 v18, v60, v19
	v_cvt_pk_bf16_f32 v18, v0, v18
	ds_read2_b32 v[20:21], v40 offset0:214 offset1:247
	s_waitcnt lgkmcnt(0)
	v_mul_f32_e32 v19, v60, v21
	v_mul_f32_e32 v0, v60, v20
	v_cvt_pk_bf16_f32 v19, v0, v19
	ds_read2_b32 v[20:21], v40 offset0:24 offset1:57
	global_store_dwordx4 v[22:23], v[16:19], off nt
	v_or_b32_e32 v22, v28, v43
	v_ashrrev_i32_e32 v23, 31, v22
	v_lshlrev_b64 v[22:23], 11, v[22:23]
	s_waitcnt lgkmcnt(0)
	v_mul_f32_e32 v16, v60, v21
	v_mul_f32_e32 v0, v60, v20
	v_cvt_pk_bf16_f32 v16, v0, v16
	ds_read2_b32 v[18:19], v40 offset0:90 offset1:123
	s_waitcnt lgkmcnt(0)
	v_mul_f32_e32 v17, v60, v19
	v_mul_f32_e32 v0, v60, v18
	v_cvt_pk_bf16_f32 v17, v0, v17
	ds_read2_b32 v[18:19], v40 offset0:156 offset1:189
	s_waitcnt lgkmcnt(0)
	v_mul_f32_e32 v0, v60, v18
	v_mul_f32_e32 v18, v60, v19
	v_cvt_pk_bf16_f32 v18, v0, v18
	ds_read2_b32 v[20:21], v40 offset0:222 offset1:255
	s_waitcnt lgkmcnt(0)
	v_mul_f32_e32 v0, v60, v20
	v_mul_f32_e32 v19, v60, v21
	v_lshl_add_u64 v[20:21], v[26:27], 0, v[22:23]
	v_cvt_pk_bf16_f32 v19, v0, v19
	global_store_dwordx4 v[20:21], v[16:19], off nt
	s_waitcnt lgkmcnt(0)
	s_branch .LBB0_29

; __device__ __forceinline__ void prologue_a(const Args& a, LAS unsigned char* lds, int tid, int G) {
;     ...
;         for (int it = blockIdx.x; it < DEPTH * 72; it += G) {
;             const int l = it / 72, cb = it % 72, col = cb * 128 + jj;
;             const float* wp = a.in[I_WMOD] + (size_t)l * DM * 9216 + col;
;             float acc[9];
; #pragma unroll
;             for (int m = 0; m < 9; ++m) acc[m] = 0.f;
; #pragma unroll 4
;             for (int k = kq * 256; k < kq * 256 + 256; ++k) {
;                 const float w = __builtin_nontemporal_load(wp + (size_t)k * 9216);
; #pragma unroll
;                 for (int m = 0; m < 9; ++m) acc[m] += sc[m * 1024 + k] * w;
.LBB0_61:
	s_mul_hi_i32 s0, s3, 0x38e38e39
	s_lshr_b32 s1, s0, 31
	s_ashr_i32 s0, s0, 4
	s_add_i32 s9, s0, s1
	s_mul_i32 s0, s9, 0x48
	s_sub_i32 s0, s3, s0
	s_lshl_b32 s8, s0, 7
	v_or_b32_e32 v6, s8, v16
	v_ashrrev_i32_e32 v7, 31, v6
	v_lshlrev_b64 v[6:7], 2, v[6:7]
	v_mad_i64_i32 v[6:7], s[0:1], s9, v201, v[6:7]
	v_mov_b32_e32 v8, 0
	v_lshl_add_u64 v[6:7], v[4:5], 0, v[6:7]
	s_mov_b64 s[10:11], 0
	v_mov_b32_e32 v20, v0
	v_mov_b32_e32 v9, v8
	v_mov_b32_e32 v10, v8
	v_mov_b32_e32 v11, v8
	v_mov_b32_e32 v12, v8
	v_mov_b32_e32 v13, v8
	v_mov_b32_e32 v14, v8
	v_mov_b32_e32 v15, v8
	v_mov_b32_e32 v21, v8
	s_mov_b32 s0, 0x9000
	s_mov_b32 s1, 0
.LBB0_62:
	v_lshl_add_u64 v[110:111], v[6:7], 0, s[10:11]
	global_load_dword v78, v[110:111], off nt
	v_lshl_add_u64 v[112:113], v[110:111], 0, s[0:1]
	global_load_dword v80, v[112:113], off nt
	v_lshl_add_u64 v[114:115], v[112:113], 0, s[0:1]
	global_load_dword v82, v[114:115], off nt
	v_lshl_add_u64 v[116:117], v[114:115], 0, s[0:1]
	global_load_dword v84, v[116:117], off nt
	v_lshl_add_u64 v[110:111], v[116:117], 0, s[0:1]
	global_load_dword v86, v[110:111], off nt
	v_lshl_add_u64 v[112:113], v[110:111], 0, s[0:1]
	global_load_dword v88, v[112:113], off nt
	v_lshl_add_u64 v[114:115], v[112:113], 0, s[0:1]
	global_load_dword v90, v[114:115], off nt
	v_lshl_add_u64 v[116:117], v[114:115], 0, s[0:1]
	global_load_dword v92, v[116:117], off nt
	v_lshl_add_u64 v[110:111], v[116:117], 0, s[0:1]
	global_load_dword v94, v[110:111], off nt
	v_lshl_add_u64 v[112:113], v[110:111], 0, s[0:1]
	global_load_dword v96, v[112:113], off nt
	v_lshl_add_u64 v[114:115], v[112:113], 0, s[0:1]
	global_load_dword v98, v[114:115], off nt
	v_lshl_add_u64 v[116:117], v[114:115], 0, s[0:1]
	global_load_dword v100, v[116:117], off nt
	v_lshl_add_u64 v[110:111], v[116:117], 0, s[0:1]
	global_load_dword v102, v[110:111], off nt
	v_lshl_add_u64 v[112:113], v[110:111], 0, s[0:1]
	global_load_dword v104, v[112:113], off nt
	v_lshl_add_u64 v[114:115], v[112:113], 0, s[0:1]
	global_load_dword v106, v[114:115], off nt
	v_lshl_add_u64 v[116:117], v[114:115], 0, s[0:1]
	global_load_dword v108, v[116:117], off nt
	s_add_u32 s10, s10, 0x90000
	s_addc_u32 s11, s11, 0
	ds_read_b128 v[22:25], v20 offset:4096
	ds_read_b128 v[26:29], v20 offset:8192
	ds_read_b128 v[30:33], v20 offset:12288
	ds_read_b128 v[34:37], v20 offset:16384
	ds_read_b128 v[40:43], v20 offset:20480
	ds_read_b128 v[44:47], v20 offset:24576
	ds_read_b128 v[48:51], v20 offset:28672
	ds_read_b128 v[52:55], v20
	ds_read_b128 v[56:59], v20 offset:32768
	s_waitcnt lgkmcnt(8)
	v_mov_b32_e32 v69, v22
	s_waitcnt lgkmcnt(7)
	v_mov_b32_e32 v70, v26
	s_waitcnt lgkmcnt(6)
	v_mov_b32_e32 v71, v30
	s_waitcnt lgkmcnt(1)
	v_mov_b32_e32 v68, v52
	v_mov_b32_e32 v72, v34
	v_mov_b32_e32 v73, v40
	v_mov_b32_e32 v74, v44
	v_mov_b32_e32 v75, v48
	v_mov_b32_e32 v22, v53
	v_mov_b32_e32 v30, v27
	v_mov_b32_e32 v40, v35
	v_mov_b32_e32 v48, v45
	v_mov_b32_e32 v26, v54
	v_mov_b32_e32 v27, v24
	v_mov_b32_e32 v34, v28
	v_mov_b32_e32 v35, v32
	v_mov_b32_e32 v44, v36
	v_mov_b32_e32 v45, v42
	v_mov_b32_e32 v52, v46
	v_mov_b32_e32 v53, v50
	v_mov_b32_e32 v24, v55
	v_mov_b32_e32 v32, v29
	v_mov_b32_e32 v42, v37
	v_mov_b32_e32 v50, v47
	v_add_u32_e32 v20, 16, v20
	s_waitcnt vmcnt(15)
	v_pk_fma_f32 v[8:9], v[78:79], v[68:69], v[8:9] op_sel_hi:[0,1,1]
	v_pk_fma_f32 v[10:11], v[78:79], v[70:71], v[10:11] op_sel_hi:[0,1,1]
	v_pk_fma_f32 v[12:13], v[78:79], v[72:73], v[12:13] op_sel_hi:[0,1,1]
	v_pk_fma_f32 v[14:15], v[78:79], v[74:75], v[14:15] op_sel_hi:[0,1,1]
	s_waitcnt lgkmcnt(0)
	v_fmac_f32_e32 v21, v78, v56
	s_waitcnt vmcnt(14)
	v_pk_fma_f32 v[8:9], v[80:81], v[22:23], v[8:9] op_sel_hi:[0,1,1]
	v_pk_fma_f32 v[10:11], v[80:81], v[30:31], v[10:11] op_sel_hi:[0,1,1]
	v_pk_fma_f32 v[12:13], v[80:81], v[40:41], v[12:13] op_sel_hi:[0,1,1]
	v_pk_fma_f32 v[14:15], v[80:81], v[48:49], v[14:15] op_sel_hi:[0,1,1]
	v_fmac_f32_e32 v21, v80, v57
	s_waitcnt vmcnt(13)
	v_pk_fma_f32 v[8:9], v[82:83], v[26:27], v[8:9] op_sel_hi:[0,1,1]
	v_pk_fma_f32 v[10:11], v[82:83], v[34:35], v[10:11] op_sel_hi:[0,1,1]
	v_pk_fma_f32 v[12:13], v[82:83], v[44:45], v[12:13] op_sel_hi:[0,1,1]
	v_pk_fma_f32 v[14:15], v[82:83], v[52:53], v[14:15] op_sel_hi:[0,1,1]
	v_fmac_f32_e32 v21, v82, v58
	s_waitcnt vmcnt(12)
	v_pk_fma_f32 v[8:9], v[84:85], v[24:25], v[8:9] op_sel_hi:[0,1,1]
	v_pk_fma_f32 v[10:11], v[84:85], v[32:33], v[10:11] op_sel_hi:[0,1,1]
	v_pk_fma_f32 v[12:13], v[84:85], v[42:43], v[12:13] op_sel_hi:[0,1,1]
	v_pk_fma_f32 v[14:15], v[84:85], v[50:51], v[14:15] op_sel_hi:[0,1,1]
	v_fmac_f32_e32 v21, v84, v59
	ds_read_b128 v[22:25], v20 offset:4096
	ds_read_b128 v[26:29], v20 offset:8192
	ds_read_b128 v[30:33], v20 offset:12288
	ds_read_b128 v[34:37], v20 offset:16384
	ds_read_b128 v[40:43], v20 offset:20480
	ds_read_b128 v[44:47], v20 offset:24576
	ds_read_b128 v[48:51], v20 offset:28672
	ds_read_b128 v[52:55], v20
	ds_read_b128 v[56:59], v20 offset:32768
	s_waitcnt lgkmcnt(8)
	v_mov_b32_e32 v69, v22
	s_waitcnt lgkmcnt(7)
	v_mov_b32_e32 v70, v26
	s_waitcnt lgkmcnt(6)
	v_mov_b32_e32 v71, v30
	s_waitcnt lgkmcnt(1)
	v_mov_b32_e32 v68, v52
	v_mov_b32_e32 v72, v34
	v_mov_b32_e32 v73, v40
	v_mov_b32_e32 v74, v44
	v_mov_b32_e32 v75, v48
	v_mov_b32_e32 v22, v53
	v_mov_b32_e32 v30, v27
	v_mov_b32_e32 v40, v35
	v_mov_b32_e32 v48, v45
	v_mov_b32_e32 v26, v54
	v_mov_b32_e32 v27, v24
	v_mov_b32_e32 v34, v28
	v_mov_b32_e32 v35, v32
	v_mov_b32_e32 v44, v36
	v_mov_b32_e32 v45, v42
	v_mov_b32_e32 v52, v46
	v_mov_b32_e32 v53, v50
	v_mov_b32_e32 v24, v55
	v_mov_b32_e32 v32, v29
	v_mov_b32_e32 v42, v37
	v_mov_b32_e32 v50, v47
	v_add_u32_e32 v20, 16, v20
	s_waitcnt vmcnt(11)
; __device__ __forceinline__ void prologue_a(const Args& a, LAS unsigned char* lds, int tid, int G) {
;     ...
;             for (int k = kq * 256; k < kq * 256 + 256; ++k) {
;                 const float w = __builtin_nontemporal_load(wp + (size_t)k * 9216);
; #pragma unroll
;                 for (int m = 0; m < 9; ++m) acc[m] += sc[m * 1024 + k] * w;
;             }
; #pragma unroll
;             for (int m = 0; m < 9; ++m) red[(kq * 9 + m) * 128 + jj] = acc[m];
;             __syncthreads();
;             for (int o = tid; o < 9 * 128; o += 512) { const int m = o >> 7, j2 = o & 127;
;                 const float v = red[(0 * 9 + m) * 128 + j2] + red[(1 * 9 + m) * 128 + j2] + red[(2 * 9 + m) * 128 + j2] + red[(3 * 9 + m) * 128 + j2];
;                 MOD[((size_t)l * 9 + m) * 9216 + cb * 128 + j2] = v + a.in[I_BMOD][l * 9216 + cb * 128 + j2]; }
	v_pk_fma_f32 v[8:9], v[86:87], v[68:69], v[8:9] op_sel_hi:[0,1,1]
	v_pk_fma_f32 v[10:11], v[86:87], v[70:71], v[10:11] op_sel_hi:[0,1,1]
	v_pk_fma_f32 v[12:13], v[86:87], v[72:73], v[12:13] op_sel_hi:[0,1,1]
	v_pk_fma_f32 v[14:15], v[86:87], v[74:75], v[14:15] op_sel_hi:[0,1,1]
	s_waitcnt lgkmcnt(0)
	v_fmac_f32_e32 v21, v86, v56
	s_waitcnt vmcnt(10)
	v_pk_fma_f32 v[8:9], v[88:89], v[22:23], v[8:9] op_sel_hi:[0,1,1]
	v_pk_fma_f32 v[10:11], v[88:89], v[30:31], v[10:11] op_sel_hi:[0,1,1]
	v_pk_fma_f32 v[12:13], v[88:89], v[40:41], v[12:13] op_sel_hi:[0,1,1]
	v_pk_fma_f32 v[14:15], v[88:89], v[48:49], v[14:15] op_sel_hi:[0,1,1]
	v_fmac_f32_e32 v21, v88, v57
	s_waitcnt vmcnt(9)
	v_pk_fma_f32 v[8:9], v[90:91], v[26:27], v[8:9] op_sel_hi:[0,1,1]
	v_pk_fma_f32 v[10:11], v[90:91], v[34:35], v[10:11] op_sel_hi:[0,1,1]
	v_pk_fma_f32 v[12:13], v[90:91], v[44:45], v[12:13] op_sel_hi:[0,1,1]
	v_pk_fma_f32 v[14:15], v[90:91], v[52:53], v[14:15] op_sel_hi:[0,1,1]
	v_fmac_f32_e32 v21, v90, v58
	s_waitcnt vmcnt(8)
	v_pk_fma_f32 v[8:9], v[92:93], v[24:25], v[8:9] op_sel_hi:[0,1,1]
	v_pk_fma_f32 v[10:11], v[92:93], v[32:33], v[10:11] op_sel_hi:[0,1,1]
	v_pk_fma_f32 v[12:13], v[92:93], v[42:43], v[12:13] op_sel_hi:[0,1,1]
	v_pk_fma_f32 v[14:15], v[92:93], v[50:51], v[14:15] op_sel_hi:[0,1,1]
	v_fmac_f32_e32 v21, v92, v59
	ds_read_b128 v[22:25], v20 offset:4096
	ds_read_b128 v[26:29], v20 offset:8192
	ds_read_b128 v[30:33], v20 offset:12288
	ds_read_b128 v[34:37], v20 offset:16384
	ds_read_b128 v[40:43], v20 offset:20480
	ds_read_b128 v[44:47], v20 offset:24576
	ds_read_b128 v[48:51], v20 offset:28672
	ds_read_b128 v[52:55], v20
	ds_read_b128 v[56:59], v20 offset:32768
	s_waitcnt lgkmcnt(8)
	v_mov_b32_e32 v69, v22
	s_waitcnt lgkmcnt(7)
	v_mov_b32_e32 v70, v26
	s_waitcnt lgkmcnt(6)
	v_mov_b32_e32 v71, v30
	s_waitcnt lgkmcnt(1)
	v_mov_b32_e32 v68, v52
	v_mov_b32_e32 v72, v34
	v_mov_b32_e32 v73, v40
	v_mov_b32_e32 v74, v44
	v_mov_b32_e32 v75, v48
	v_mov_b32_e32 v22, v53
	v_mov_b32_e32 v30, v27
	v_mov_b32_e32 v40, v35
	v_mov_b32_e32 v48, v45
	v_mov_b32_e32 v26, v54
	v_mov_b32_e32 v27, v24
	v_mov_b32_e32 v34, v28
	v_mov_b32_e32 v35, v32
	v_mov_b32_e32 v44, v36
	v_mov_b32_e32 v45, v42
	v_mov_b32_e32 v52, v46
	v_mov_b32_e32 v53, v50
	v_mov_b32_e32 v24, v55
	v_mov_b32_e32 v32, v29
	v_mov_b32_e32 v42, v37
	v_mov_b32_e32 v50, v47
	v_add_u32_e32 v20, 16, v20
	s_waitcnt vmcnt(7)
	v_pk_fma_f32 v[8:9], v[94:95], v[68:69], v[8:9] op_sel_hi:[0,1,1]
	v_pk_fma_f32 v[10:11], v[94:95], v[70:71], v[10:11] op_sel_hi:[0,1,1]
	v_pk_fma_f32 v[12:13], v[94:95], v[72:73], v[12:13] op_sel_hi:[0,1,1]
	v_pk_fma_f32 v[14:15], v[94:95], v[74:75], v[14:15] op_sel_hi:[0,1,1]
	s_waitcnt lgkmcnt(0)
	v_fmac_f32_e32 v21, v94, v56
	s_waitcnt vmcnt(6)
	v_pk_fma_f32 v[8:9], v[96:97], v[22:23], v[8:9] op_sel_hi:[0,1,1]
	v_pk_fma_f32 v[10:11], v[96:97], v[30:31], v[10:11] op_sel_hi:[0,1,1]
	v_pk_fma_f32 v[12:13], v[96:97], v[40:41], v[12:13] op_sel_hi:[0,1,1]
	v_pk_fma_f32 v[14:15], v[96:97], v[48:49], v[14:15] op_sel_hi:[0,1,1]
	v_fmac_f32_e32 v21, v96, v57
	s_waitcnt vmcnt(5)
	v_pk_fma_f32 v[8:9], v[98:99], v[26:27], v[8:9] op_sel_hi:[0,1,1]
	v_pk_fma_f32 v[10:11], v[98:99], v[34:35], v[10:11] op_sel_hi:[0,1,1]
	v_pk_fma_f32 v[12:13], v[98:99], v[44:45], v[12:13] op_sel_hi:[0,1,1]
	v_pk_fma_f32 v[14:15], v[98:99], v[52:53], v[14:15] op_sel_hi:[0,1,1]
	v_fmac_f32_e32 v21, v98, v58
	s_waitcnt vmcnt(4)
	v_pk_fma_f32 v[8:9], v[100:101], v[24:25], v[8:9] op_sel_hi:[0,1,1]
	v_pk_fma_f32 v[10:11], v[100:101], v[32:33], v[10:11] op_sel_hi:[0,1,1]
	v_pk_fma_f32 v[12:13], v[100:101], v[42:43], v[12:13] op_sel_hi:[0,1,1]
	v_pk_fma_f32 v[14:15], v[100:101], v[50:51], v[14:15] op_sel_hi:[0,1,1]
	v_fmac_f32_e32 v21, v100, v59
	ds_read_b128 v[22:25], v20 offset:4096
	ds_read_b128 v[26:29], v20 offset:8192
	ds_read_b128 v[30:33], v20 offset:12288
	ds_read_b128 v[34:37], v20 offset:16384
	ds_read_b128 v[40:43], v20 offset:20480
	ds_read_b128 v[44:47], v20 offset:24576
	ds_read_b128 v[48:51], v20 offset:28672
	ds_read_b128 v[52:55], v20
	ds_read_b128 v[56:59], v20 offset:32768
	s_waitcnt lgkmcnt(8)
	v_mov_b32_e32 v69, v22
	s_waitcnt lgkmcnt(7)
	v_mov_b32_e32 v70, v26
	s_waitcnt lgkmcnt(6)
	v_mov_b32_e32 v71, v30
	s_waitcnt lgkmcnt(1)
	v_mov_b32_e32 v68, v52
	v_mov_b32_e32 v72, v34
	v_mov_b32_e32 v73, v40
	v_mov_b32_e32 v74, v44
	v_mov_b32_e32 v75, v48
	v_mov_b32_e32 v22, v53
	v_mov_b32_e32 v30, v27
	v_mov_b32_e32 v40, v35
	v_mov_b32_e32 v48, v45
	v_mov_b32_e32 v26, v54
	v_mov_b32_e32 v27, v24
	v_mov_b32_e32 v34, v28
	v_mov_b32_e32 v35, v32
	v_mov_b32_e32 v44, v36
	v_mov_b32_e32 v45, v42
	v_mov_b32_e32 v52, v46
	v_mov_b32_e32 v53, v50
	v_mov_b32_e32 v24, v55
	v_mov_b32_e32 v32, v29
	v_mov_b32_e32 v42, v37
	v_mov_b32_e32 v50, v47
	v_add_u32_e32 v20, 16, v20
	s_waitcnt vmcnt(3)
	v_pk_fma_f32 v[8:9], v[102:103], v[68:69], v[8:9] op_sel_hi:[0,1,1]
	v_pk_fma_f32 v[10:11], v[102:103], v[70:71], v[10:11] op_sel_hi:[0,1,1]
	v_pk_fma_f32 v[12:13], v[102:103], v[72:73], v[12:13] op_sel_hi:[0,1,1]
	v_pk_fma_f32 v[14:15], v[102:103], v[74:75], v[14:15] op_sel_hi:[0,1,1]
	s_waitcnt lgkmcnt(0)
	v_fmac_f32_e32 v21, v102, v56
	s_waitcnt vmcnt(2)
	v_pk_fma_f32 v[8:9], v[104:105], v[22:23], v[8:9] op_sel_hi:[0,1,1]
	v_pk_fma_f32 v[10:11], v[104:105], v[30:31], v[10:11] op_sel_hi:[0,1,1]
	v_pk_fma_f32 v[12:13], v[104:105], v[40:41], v[12:13] op_sel_hi:[0,1,1]
	v_pk_fma_f32 v[14:15], v[104:105], v[48:49], v[14:15] op_sel_hi:[0,1,1]
	v_fmac_f32_e32 v21, v104, v57
	s_waitcnt vmcnt(1)
	v_pk_fma_f32 v[8:9], v[106:107], v[26:27], v[8:9] op_sel_hi:[0,1,1]
	v_pk_fma_f32 v[10:11], v[106:107], v[34:35], v[10:11] op_sel_hi:[0,1,1]
	v_pk_fma_f32 v[12:13], v[106:107], v[44:45], v[12:13] op_sel_hi:[0,1,1]
	v_pk_fma_f32 v[14:15], v[106:107], v[52:53], v[14:15] op_sel_hi:[0,1,1]
	v_fmac_f32_e32 v21, v106, v58
	s_waitcnt vmcnt(0)
	v_pk_fma_f32 v[8:9], v[108:109], v[24:25], v[8:9] op_sel_hi:[0,1,1]
	v_pk_fma_f32 v[10:11], v[108:109], v[32:33], v[10:11] op_sel_hi:[0,1,1]
	v_pk_fma_f32 v[12:13], v[108:109], v[42:43], v[12:13] op_sel_hi:[0,1,1]
	v_pk_fma_f32 v[14:15], v[108:109], v[50:51], v[14:15] op_sel_hi:[0,1,1]
	v_fmac_f32_e32 v21, v108, v59
	s_cmp_eq_u32 s10, 0x900000
	s_cbranch_scc0 .LBB0_62
	ds_write2st64_b32 v19, v8, v9 offset0:144 offset1:146
	ds_write2st64_b32 v19, v10, v11 offset0:148 offset1:150
	ds_write2st64_b32 v19, v12, v13 offset0:152 offset1:154
	ds_write2st64_b32 v19, v14, v15 offset0:156 offset1:158
	ds_write_b32 v19, v21 offset:40960
	s_waitcnt lgkmcnt(0)
	s_barrier
	s_and_saveexec_b64 s[10:11], vcc
	s_cbranch_execz .LBB0_60
	s_mul_i32 s0, s9, 0x2400
	s_add_i32 s0, s0, s8
	v_or_b32_e32 v6, s0, v16
	s_mul_hi_i32 s13, s9, 9
	s_mul_i32 s12, s9, 9
	s_ashr_i32 s9, s8, 31
	v_ashrrev_i32_e32 v7, 31, v6
	v_lshl_add_u64 v[6:7], v[6:7], 2, s[86:87]
	v_lshl_add_u64 v[8:9], s[8:9], 2, v[2:3]
	s_mov_b64 s[8:9], 0
	v_mov_b32_e32 v10, v18
	v_mov_b32_e32 v11, v158
